# NSA: first K/V tile of the selected branch (always block 0) loaded at q-block start instead of at the branch entry
# baseline (speedup 1.0000x reference)
; #define LAS __attribute__((address_space(3)))
; DI int opaque_tid(int wv) { unsigned ones = ~0u; asm volatile("" : "+s"(ones)); int t = wv * 64 + (int)__builtin_amdgcn_mbcnt_hi(ones, __builtin_amdgcn_mbcnt_lo(ones, 0u)); asm volatile("" : "+v"(t)); return t; }
; DI f32x16 mfma32(bf16x8 a, bf16x8 b, f32x16 c) { return __builtin_amdgcn_mfma_f32_32x32x16_bf16(a, b, c, 0, 0, 0); }
; DI void nsa_attn_phase(int wv, LAS unsigned char* lds, const bf16_t* Q, const bf16_t* slab, const bf16_t* VT2, const float* gates, const bf16_t* KCMP, const bf16_t* VCMPT,
;                        const float* rel_bias, bf16_t* O) {
;     ...
;             tid = opaque_tid(wv); lane = tid & 63; const int r = lane & 31, hh = lane >> 5;
;             const int qblk = 4 * qi + ((qi & 1) ? 3 - qtr : qtr), T0 = 64 * qblk, TW = T0 + 32 * half;
;             const int tq = TW + r; const size_t token = (size_t)b * SEQ + tq;
;             const float c31 = mylut[127];
;             bf16x8 qf[4];
; #pragma unroll
;             for (int ks = 0; ks < 4; ++ks) qf[ks] = *(const bf16x8*)(Q + token * 1024 + head * 64 + 16 * ks + 8 * hh);
;             const float g0 = gates[token * 48 + head * 3], g1 = gates[token * 48 + head * 3 + 1], g2 = gates[token * 48 + head * 3 + 2];
;             f32x16 out[2] = {zero16(), zero16()};
;             const bool need_rank = qblk >= 16;
;             {
;                 const int nsub = (TW >> 9) + 1;
;                 f32x16 s4[4];
;                 float mx = NEGF;
; #pragma unroll
;                 for (int t = 0; t < 4; ++t) {
;                     if (t < nsub) {
;                         const bool farc = TW - (16 * (32 * t + 31) + 31) >= 127;
;                         s4[t] = splat16(farc ? c31 : 0.f);
;                         bf16x8 kfc[4];
; #pragma unroll
;                         for (int ks = 0; ks < 4; ++ks) kfc[ks] = *(const LAS bf16x8*)(lds + OFF_KC + (32 * t + r) * KCS + 32 * ks + 16 * hh);
; #pragma unroll
;                         for (int ks = 0; ks < 4; ++ks) s4[t] = mfma32(kfc[ks], qf[ks], s4[t]);
;                         if (!farc) {
;     ...
;                 auto gload = [&](int j) {
;                     rk = *(const u32x4*)(Ksrc + (size_t)j * 64 * 64 + (size_t)tid * 8);
;                     rv = *(const u32x4*)(Vsrc + (size_t)(tid >> 3) * VPITCH + 64 * j + (tid & 7) * 8);
.LBB0_2240:
	s_mov_b32 s0, -1
	v_mov_b32_e32 v213, v1
	v_mbcnt_lo_u32_b32 v0, s0, 0
	v_mbcnt_hi_u32_b32 v0, s0, v0
	s_lshl_b32 s0, s85, 2
	s_bitcmp0_b32 s85, 0
	s_cselect_b32 s1, s66, s67
	s_or_b32 s26, s1, s0
	v_add_u32_e32 v114, s11, v0
	s_lshl_b32 s90, s26, 6
	s_add_i32 s90, s90, s60
	v_and_b32_e32 v112, 31, v114
	v_or_b32_e32 v210, s90, v112
	v_ashrrev_i32_e32 v211, 31, v210
	v_lshl_add_u64 v[2:3], s[16:17], 0, v[210:211]
	v_bfe_u32 v97, v114, 5, 1
	v_lshlrev_b64 v[4:5], 11, v[2:3]
	v_lshl_add_u64 v[4:5], s[18:19], 0, v[4:5]
	v_lshlrev_b32_e32 v212, 4, v97
	v_lshl_add_u64 v[4:5], v[4:5], 0, v[212:213]
	flat_load_dwordx4 v[176:179], v[4:5]
	flat_load_dwordx4 v[180:183], v[4:5] offset:32
	flat_load_dwordx4 v[184:187], v[4:5] offset:64
	flat_load_dwordx4 v[188:191], v[4:5] offset:96
	v_mov_b64_e32 v[4:5], s[20:21]
	v_mad_u64_u32 v[4:5], s[0:1], v2, s41, v[4:5]
	v_mad_i32_i24 v5, v3, s41, v5
	flat_load_dwordx3 v[204:206], v[4:5]
	s_add_u32 s0, s69, 0x2000000
	s_addc_u32 s1, s84, 0
	v_lshlrev_b32_e32 v6, 4, v114
	v_mov_b32_e32 v7, 0
	v_lshl_add_u64 v[6:7], s[0:1], 0, v[6:7]
	flat_load_dwordx4 v[196:199], v[6:7]
	v_ashrrev_i32_e32 v8, 3, v114
	v_mov_b64_e32 v[6:7], s[14:15]
	v_mad_i64_i32 v[6:7], s[0:1], v8, s43, v[6:7]
	v_mov_b32_e32 v8, 0x1080
	v_mad_u64_u32 v[6:7], s[0:1], s22, v8, v[6:7]
	s_mul_i32 s0, s23, 0x1080
	s_nop 0
	v_add_u32_e32 v7, s0, v7
	v_lshlrev_b32_e32 v8, 3, v114
	v_and_b32_e32 v8, 56, v8
	v_lshlrev_b32_e32 v8, 1, v8
	v_mov_b32_e32 v9, 0
	v_lshl_add_u64 v[6:7], v[6:7], 0, v[8:9]
	flat_load_dwordx4 v[200:203], v[6:7]
	v_mov_b32_e32 v0, s57
	ds_read_b32 v113, v0 offset:508
	s_ashr_i32 s0, s90, 9
	v_add_u32_e32 v96, 0, v212
	s_cmp_gt_i32 s0, -1
	v_mul_i32_i24_e32 v0, 0xffffffc0, v97
	v_mov_b32_e32 v98, 0xf149f2ca
	s_cselect_b64 s[4:5], -1, 0
	s_cmp_lt_i32 s0, 0
	v_mad_u32_u24 v2, v112, s87, v96
	s_cbranch_scc1 .LBB0_2276
	ds_read_b128 v[4:7], v2
	s_cmpk_gt_u32 s90, 0x28d
	s_cselect_b64 vcc, -1, 0
	s_waitcnt lgkmcnt(0)
	v_cndmask_b32_e32 v64, 0, v113, vcc
	v_mov_b32_e32 v65, v64
	v_mov_b32_e32 v66, v64
	v_mov_b32_e32 v67, v64
	v_mov_b32_e32 v68, v64
	v_mov_b32_e32 v69, v64
	v_mov_b32_e32 v70, v64
	v_mov_b32_e32 v71, v64
	v_mov_b32_e32 v72, v64
	v_mov_b32_e32 v73, v64
	v_mov_b32_e32 v74, v64
	v_mov_b32_e32 v75, v64
	v_mov_b32_e32 v76, v64
	v_mov_b32_e32 v77, v64
	v_mov_b32_e32 v78, v64
	v_mov_b32_e32 v79, v64
	s_and_b64 vcc, exec, vcc
	s_waitcnt vmcnt(0)
	v_mfma_f32_32x32x16_bf16 v[64:79], v[4:7], v[176:179], v[64:79]
	ds_read_b128 v[4:7], v2 offset:32
	s_waitcnt lgkmcnt(0)
	v_mfma_f32_32x32x16_bf16 v[64:79], v[4:7], v[180:183], v[64:79]
	ds_read_b128 v[4:7], v2 offset:64
	s_waitcnt lgkmcnt(0)
	v_mfma_f32_32x32x16_bf16 v[64:79], v[4:7], v[184:187], v[64:79]
	ds_read_b128 v[4:7], v2 offset:96
	s_waitcnt lgkmcnt(0)
	v_mfma_f32_32x32x16_bf16 v[64:79], v[4:7], v[188:191], v[64:79]
	s_cbranch_vccnz .LBB0_2275
	s_movk_i32 s1, 0xffe1
	v_add3_u32 v3, v210, v0, s1
	v_mov_b32_e32 v4, 0xffffffc0
	v_mov_b32_e32 v5, 0x1ff
	v_med3_i32 v80, v3, v4, v5
	v_lshl_add_u32 v80, v80, 2, s71
	ds_read_b32 v80, v80
	v_add_u32_e32 v81, 0xfffffff0, v3
	v_med3_i32 v81, v81, v4, v5
	v_lshl_add_u32 v81, v81, 2, s71
	ds_read_b32 v81, v81
	v_add_u32_e32 v82, 0xffffffe0, v3
	v_med3_i32 v82, v82, v4, v5
	v_lshl_add_u32 v82, v82, 2, s71
	ds_read_b32 v82, v82
	v_add_u32_e32 v83, 0xffffffd0, v3
	v_med3_i32 v83, v83, v4, v5
	v_lshl_add_u32 v83, v83, 2, s71
	ds_read_b32 v83, v83
	v_add_u32_e32 v84, 0xffffff80, v3
	v_med3_i32 v84, v84, v4, v5
	v_lshl_add_u32 v84, v84, 2, s71
	ds_read_b32 v84, v84
	v_add_u32_e32 v85, 0xffffff70, v3
	v_med3_i32 v85, v85, v4, v5
	v_lshl_add_u32 v85, v85, 2, s71
	ds_read_b32 v85, v85
	v_add_u32_e32 v86, 0xffffff60, v3
	v_med3_i32 v86, v86, v4, v5
	v_lshl_add_u32 v86, v86, 2, s71
	ds_read_b32 v86, v86
	v_add_u32_e32 v87, 0xffffff50, v3
	v_med3_i32 v87, v87, v4, v5
	v_lshl_add_u32 v87, v87, 2, s71
	ds_read_b32 v87, v87
	v_add_u32_e32 v88, 0xffffff00, v3
	v_med3_i32 v88, v88, v4, v5
	v_lshl_add_u32 v88, v88, 2, s71
	ds_read_b32 v88, v88
	v_add_u32_e32 v89, 0xfffffef0, v3
	v_med3_i32 v89, v89, v4, v5
	v_lshl_add_u32 v89, v89, 2, s71
	ds_read_b32 v89, v89
	v_add_u32_e32 v90, 0xfffffee0, v3
	v_med3_i32 v90, v90, v4, v5
	v_lshl_add_u32 v90, v90, 2, s71
	ds_read_b32 v90, v90
	v_add_u32_e32 v91, 0xfffffed0, v3
	v_med3_i32 v91, v91, v4, v5
	v_lshl_add_u32 v91, v91, 2, s71
	ds_read_b32 v91, v91
	v_add_u32_e32 v92, 0xfffffe80, v3
	v_med3_i32 v92, v92, v4, v5
	v_lshl_add_u32 v92, v92, 2, s71
	ds_read_b32 v92, v92
	v_add_u32_e32 v93, 0xfffffe70, v3
	v_med3_i32 v93, v93, v4, v5
	v_lshl_add_u32 v93, v93, 2, s71
	ds_read_b32 v93, v93
	v_add_u32_e32 v94, 0xfffffe60, v3
	v_med3_i32 v94, v94, v4, v5
	v_lshl_add_u32 v94, v94, 2, s71
	ds_read_b32 v94, v94
	v_add_u32_e32 v95, 0xfffffe50, v3
	v_med3_i32 v95, v95, v4, v5
	v_lshl_add_u32 v95, v95, 2, s71
	ds_read_b32 v95, v95
	s_waitcnt lgkmcnt(15)
	v_add_f32_e32 v64, v64, v80
	s_waitcnt lgkmcnt(14)
	v_add_f32_e32 v65, v65, v81
	s_waitcnt lgkmcnt(13)
	v_add_f32_e32 v66, v66, v82
	s_waitcnt lgkmcnt(12)
	v_add_f32_e32 v67, v67, v83
	s_waitcnt lgkmcnt(11)
	v_add_f32_e32 v68, v68, v84
	s_waitcnt lgkmcnt(10)
	v_add_f32_e32 v69, v69, v85
	s_waitcnt lgkmcnt(9)
	v_add_f32_e32 v70, v70, v86
	s_waitcnt lgkmcnt(8)
	v_add_f32_e32 v71, v71, v87
	s_waitcnt lgkmcnt(7)
	v_add_f32_e32 v72, v72, v88
	s_waitcnt lgkmcnt(6)
	v_add_f32_e32 v73, v73, v89
	s_waitcnt lgkmcnt(5)
	v_add_f32_e32 v74, v74, v90
	s_waitcnt lgkmcnt(4)
	v_add_f32_e32 v75, v75, v91
	s_waitcnt lgkmcnt(3)
	v_add_f32_e32 v76, v76, v92
	s_waitcnt lgkmcnt(2)
	v_add_f32_e32 v77, v77, v93
	s_waitcnt lgkmcnt(1)
	v_add_f32_e32 v78, v78, v94
	s_waitcnt lgkmcnt(0)
	v_add_f32_e32 v79, v79, v95

; #define LAS __attribute__((address_space(3)))
; DI void nsa_attn_phase(int wv, LAS unsigned char* lds, const bf16_t* Q, const bf16_t* slab, const bf16_t* VT2, const float* gates, const bf16_t* KCMP, const bf16_t* VCMPT,
;                        const float* rel_bias, bf16_t* O) {
;     ...
;                 const bf16_t* Ksrc = slab + (size_t)(br ? 3 : 2) * SLAB_EL + bg * 2048 * 64;
;                 const bf16_t* Vsrc = VT2 + ((size_t)b * 512 + (br ? 256 : 0) + g * 64) * VPITCH;
;                 unsigned tiles;
;                 if (br == 0) tiles = uni; else { const int jlo = qblk - 8 < 0 ? 0 : qblk - 8; tiles = causal & ~((1u << jlo) - 1u); }
;                 float m = 0.f, l = 0.f; f32x16 o[2] = {zero16(), zero16()};
;                 u32x4 rk, rv;
;                 auto gload = [&](int j) {
;                     rk = *(const u32x4*)(Ksrc + (size_t)j * 64 * 64 + (size_t)tid * 8);
;                     rv = *(const u32x4*)(Vsrc + (size_t)(tid >> 3) * VPITCH + 64 * j + (tid & 7) * 8);
;                 };
;                 auto lstore = [&](int buf) {
;                     LAS unsigned char* kb = lds + OFF_BUF + buf * TILE;
;                     *(LAS u32x4*)(kb + (tid >> 3) * KS + (tid & 7) * 16) = rk;
;                     lds_store16_as2x8(kb + VOFF + (tid >> 3) * VS + (tid & 7) * 16, rv);
;                 };
;                 auto process = [&](const LAS unsigned char* kb, int j) {
;                     const int k0 = 64 * j;
;                     const bool selbit = (br == 0) ? (((mysel >> j) & 1u) != 0u) : true;
;                     if (br == 0 && __ballot(selbit) == 0ull) return;
;                     const bool far = (TW - (k0 + 63) >= 127) && (br == 0 || (TW + 31 - k0 < 512));
;                     f32x16 s[2];
;                     qk_tile<4>(kb, KS, qf, s, r, hh, ref_frag(-m, far ? (selbit ? c31 : NEGF) : 0.f, hh));
;                     if (!far) {
;                         const int d0 = tq - k0 - 4 * hh;
; #pragma unroll
;                         for (int t = 0; t < 2; ++t)
; #pragma unroll
;                             for (int i = 0; i < 16; ++i) {
;                                 const int dist = d0 - (32 * t + (i & 3) + 8 * (i >> 2));
;                                 const float bias = mylut[dist < 0 ? 0 : (dist > 127 ? 127 : dist)];
;                                 const bool valid = selbit && dist >= 0 && (br == 0 || dist < 512);
.LBB0_2416:
	s_and_b64 s[0:1], s[8:9], exec
	s_brev_b32 s0, 64
	s_cselect_b32 s0, s0, 0x3000000
	v_mov_b32_e32 v0, s91
	s_add_u32 s4, s69, s0
	v_cndmask_b32_e64 v0, v0, v234, s[8:9]
	s_addc_u32 s5, s84, 0
	v_ffbl_b32_e32 v144, v0
	v_add_u32_e32 v2, -1, v0
	s_and_b64 s[0:1], s[8:9], exec
	v_and_b32_e32 v4, v2, v0
	v_lshlrev_b32_e32 v0, 13, v144
	s_cselect_b32 s0, 0, 0x100
	v_lshl_add_u64 v[2:3], s[4:5], 0, v[0:1]
	s_or_b32 s0, s0, s22
	v_lshl_add_u64 v[2:3], v[2:3], 0, v[214:215]
	v_mov_b32_e32 v0, 0x1080
	s_waitcnt vmcnt(0)
	s_cmp_lg_u64 s[8:9], 0
	s_cbranch_scc1 .Lnsa_ft_k
	flat_load_dwordx4 v[196:199], v[2:3]
.Lnsa_ft_k:
	v_mad_u64_u32 v[2:3], s[0:1], s0, v0, v[216:217]
	s_mul_i32 s0, s23, 0x1080
	s_nop 0
	v_add_u32_e32 v3, s0, v3
	v_lshlrev_b32_e32 v0, 7, v144
	v_lshl_add_u64 v[6:7], v[2:3], 0, v[0:1]
	v_lshlrev_b32_e32 v0, 1, v204
	v_lshl_add_u64 v[6:7], v[6:7], 0, v[0:1]
	s_cmp_lg_u64 s[8:9], 0
	s_cbranch_scc1 .Lnsa_ft_v
	flat_load_dwordx4 v[200:203], v[6:7]
.Lnsa_ft_v:
	v_mov_b32_e32 v244, -1
	v_add_u32_e32 v5, v237, v238
	v_cmp_ne_u32_e32 vcc, 0, v4
	v_mov_b32_e32 v245, 0
	v_mov_b32_e32 v145, 0
	s_waitcnt vmcnt(0) lgkmcnt(0)
	ds_write_b128 v5, v[196:199] offset:35328
	ds_write2_b64 v243, v[200:201], v[202:203] offset1:2
	s_and_saveexec_b64 s[6:7], vcc
	s_cbranch_execz .LBB0_2418
	v_ffbl_b32_e32 v244, v4
	v_lshlrev_b32_e32 v6, 13, v244
	v_mov_b32_e32 v7, v1
	v_lshl_add_u64 v[6:7], s[4:5], 0, v[6:7]
	v_lshlrev_b32_e32 v8, 7, v244
	v_mov_b32_e32 v9, v1
	v_lshl_add_u64 v[6:7], v[6:7], 0, v[214:215]
	v_lshl_add_u64 v[8:9], v[2:3], 0, v[8:9]
	v_lshl_add_u64 v[8:9], v[8:9], 0, v[0:1]
	flat_load_dwordx4 v[196:199], v[6:7]
	flat_load_dwordx4 v[200:203], v[8:9]
	v_add_u32_e32 v5, -1, v4
	v_and_b32_e32 v145, v5, v4
